# same as previous; static LDS back to the baseline size 143376 (epilogue scratch now fits below it), clean lint
# speedup vs baseline: 1.1971x; 1.0040x over previous
	.amdhsa_kernel _Z4mega1Piii
		.amdhsa_group_segment_fixed_size 143376
		.amdhsa_private_segment_fixed_size 0
		.amdhsa_kernarg_size 568
		.amdhsa_user_sgpr_count 2
		.amdhsa_user_sgpr_dispatch_ptr 0
		.amdhsa_user_sgpr_queue_ptr 0
		.amdhsa_user_sgpr_kernarg_segment_ptr 1
		.amdhsa_user_sgpr_dispatch_id 0
		.amdhsa_user_sgpr_kernarg_preload_length 0
		.amdhsa_user_sgpr_kernarg_preload_offset 0
		.amdhsa_user_sgpr_private_segment_size 0
		.amdhsa_uses_dynamic_stack 0
		.amdhsa_enable_private_segment 0
		.amdhsa_system_sgpr_workgroup_id_x 1
		.amdhsa_system_sgpr_workgroup_id_y 0
		.amdhsa_system_sgpr_workgroup_id_z 0
		.amdhsa_system_sgpr_workgroup_info 0
		.amdhsa_system_vgpr_workitem_id 2
		.amdhsa_next_free_vgpr 238
		.amdhsa_next_free_sgpr 102
		.amdhsa_accum_offset 240
		.amdhsa_reserve_vcc 1
		.amdhsa_float_round_mode_32 0
		.amdhsa_float_round_mode_16_64 0
		.amdhsa_float_denorm_mode_32 3
		.amdhsa_float_denorm_mode_16_64 3
		.amdhsa_dx10_clamp 1
		.amdhsa_ieee_mode 1
		.amdhsa_fp16_overflow 0
		.amdhsa_tg_split 0
		.amdhsa_exception_fp_ieee_invalid_op 0
		.amdhsa_exception_fp_denorm_src 0
		.amdhsa_exception_fp_ieee_div_zero 0
		.amdhsa_exception_fp_ieee_overflow 0
		.amdhsa_exception_fp_ieee_underflow 0
		.amdhsa_exception_fp_ieee_inexact 0
		.amdhsa_exception_int_div_zero 0
	.end_amdhsa_kernel

amdhsa.kernels:
  - .agpr_count:     0
    .args:
      - .offset:         0
        .size:           296
        .value_kind:     by_value
      - .offset:         296
        .size:           4
        .value_kind:     by_value
      - .offset:         300
        .size:           4
        .value_kind:     by_value
      - .offset:         304
        .size:           4
        .value_kind:     by_value
      - .offset:         312
        .size:           4
        .value_kind:     hidden_block_count_x
      - .offset:         316
        .size:           4
        .value_kind:     hidden_block_count_y
      - .offset:         320
        .size:           4
        .value_kind:     hidden_block_count_z
      - .offset:         324
        .size:           2
        .value_kind:     hidden_group_size_x
      - .offset:         326
        .size:           2
        .value_kind:     hidden_group_size_y
      - .offset:         328
        .size:           2
        .value_kind:     hidden_group_size_z
      - .offset:         330
        .size:           2
        .value_kind:     hidden_remainder_x
      - .offset:         332
        .size:           2
        .value_kind:     hidden_remainder_y
      - .offset:         334
        .size:           2
        .value_kind:     hidden_remainder_z
      - .offset:         352
        .size:           8
        .value_kind:     hidden_global_offset_x
      - .offset:         360
        .size:           8
        .value_kind:     hidden_global_offset_y
      - .offset:         368
        .size:           8
        .value_kind:     hidden_global_offset_z
      - .offset:         376
        .size:           2
        .value_kind:     hidden_grid_dims
      - .offset:         400
        .size:           8
        .value_kind:     hidden_multigrid_sync_arg
    .group_segment_fixed_size: 143376
    .kernarg_segment_align: 8
    .kernarg_segment_size: 568
    .language:       OpenCL C
    .language_version:
      - 2
      - 0
    .max_flat_workgroup_size: 512
    .name:           _Z4mega1Piii
    .private_segment_fixed_size: 0
    .sgpr_count:     108
    .sgpr_spill_count: 197
    .symbol:         _Z4mega1Piii.kd
    .uniform_work_group_size: 1
    .uses_dynamic_stack: false
    .vgpr_count:     238
    .vgpr_spill_count: 0
    .wavefront_size: 64
